# in-proj layer-1 XCD permutation variant: the T group's round staggered across XCDs (round x mod 3)
# baseline (speedup 1.0000x reference)
;     __device__ __forceinline__ bool idx(int i, int& Lp, int& half) const {
;         const int R = n / G, T = n % G; long L; half = 0;
;         if (i == R && T > 0 && 2 * T <= G) { if (c >= 2 * T) return false; L = (long)R * G + (c >> 1); half = 1 + (c & 1); }
;         else { L = (long)i * G + c; if (L >= n) return false; }
;         const int w = (int)L, q = n / 8, r = n % 8, xcd = w % 8, off = w / 8;
;         Lp = (xcd < r ? xcd * (q + 1) : r * (q + 1) + (xcd - r) * q) + off; return true;
;     __device__ __forceinline__ bool next(int i, Unit& u) const {
;     ...
;         if (!l1) { if (q < 504) { kind = 0; const int gid = q / 56, rem = q % 56; pm = gid * 8 + (rem & 7); pn = rem >> 3; } else if (q < 760) { const int s = q - 504; kind = 1; bt = s >> 5; pn = (s & 31) >> 2; pm = s & 3; } else { const int s = q - 760; kind = 2; bt = s >> 2; pm = s & 3; pn = 0; } }
;         else { if (q < 448) { kind = 0; const int gid = q / 56, rem = q % 56; pm = gid * 8 + (rem & 7); pn = rem >> 3; } else if (q < 488) { const int s = q - 448, r5 = s % 5; kind = 0; pm = 64 + s / 5; pn = r5 < 4 ? r5 + 1 : 6; }
;                else if (q < 744) { const int s = q - 488; kind = 1; bt = s >> 5; pn = (s & 31) >> 2; pm = s & 3; } else { const int s = q - 744; kind = 2; bt = s / 3; pm = 1 + s % 3; pn = 0; } }
.LBB0_375:
	v_readlane_b32 s10, v255, 20
	v_readlane_b32 s11, v255, 21
	s_mov_b64 s[4:5], -1
	s_and_b64 vcc, exec, s[10:11]
	s_cbranch_vccz .LBB0_387
	s_lshr_b32 s18, s19, 5
	s_mul_i32 s20, s18, 11
	s_lshr_b32 s20, s20, 5
	s_mul_i32 s22, s20, 3
	s_sub_i32 s22, s18, s22
	s_cmp_lt_u32 s20, 6
	s_cbranch_scc0 .Lperm_hi_a
	s_mul_i32 s18, s20, 11
	s_lshr_b32 s18, s18, 5
	s_mul_i32 s18, s18, 3
	s_sub_i32 s18, s20, s18
	s_add_i32 s23, s20, 14
	s_cmp_eq_u32 s22, s18
	s_cbranch_scc1 .Lperm_done_a
	s_cmp_gt_u32 s22, s18
	s_cselect_b32 s18, 1, 0
	s_sub_i32 s22, s22, s18
	s_lshl_b32 s23, s20, 1
	s_add_i32 s23, s23, s22
	s_branch .Lperm_done_a
.Lperm_hi_a:
	s_lshl_b32 s23, s20, 1
	s_add_i32 s23, s23, s22
	s_add_i32 s18, s20, 6
	s_add_i32 s23, s23, 7
	s_cmp_eq_u32 s22, 0
	s_cselect_b32 s23, s18, s23

;     __device__ __forceinline__ bool idx(int i, int& Lp, int& half) const {
;         const int R = n / G, T = n % G; long L; half = 0;
;         if (i == R && T > 0 && 2 * T <= G) { if (c >= 2 * T) return false; L = (long)R * G + (c >> 1); half = 1 + (c & 1); }
;         else { L = (long)i * G + c; if (L >= n) return false; }
;         const int w = (int)L, q = n / 8, r = n % 8, xcd = w % 8, off = w / 8;
;         Lp = (xcd < r ? xcd * (q + 1) : r * (q + 1) + (xcd - r) * q) + off; return true;
;     __device__ __forceinline__ bool next(int i, Unit& u) const {
;     ...
;         if (!l1) { if (q < 504) { kind = 0; const int gid = q / 56, rem = q % 56; pm = gid * 8 + (rem & 7); pn = rem >> 3; } else if (q < 760) { const int s = q - 504; kind = 1; bt = s >> 5; pn = (s & 31) >> 2; pm = s & 3; } else { const int s = q - 760; kind = 2; bt = s >> 2; pm = s & 3; pn = 0; } }
;         else { if (q < 448) { kind = 0; const int gid = q / 56, rem = q % 56; pm = gid * 8 + (rem & 7); pn = rem >> 3; } else if (q < 488) { const int s = q - 448, r5 = s % 5; kind = 0; pm = 64 + s / 5; pn = r5 < 4 ? r5 + 1 : 6; }
;                else if (q < 744) { const int s = q - 488; kind = 1; bt = s >> 5; pn = (s & 31) >> 2; pm = s & 3; } else { const int s = q - 744; kind = 2; bt = s / 3; pm = 1 + s % 3; pn = 0; } }
.LBB0_415:
	s_xor_b64 s[26:27], s[30:31], -1
	s_and_b64 vcc, exec, s[26:27]
	s_mov_b64 s[36:37], s[14:15]
	s_mov_b64 s[34:35], s[10:11]
	s_cbranch_vccnz .LBB0_446
	v_readlane_b32 s12, v255, 20
	v_readlane_b32 s13, v255, 21
	s_mov_b64 s[4:5], -1
	s_and_b64 vcc, exec, s[12:13]
	s_cbranch_vccz .LBB0_428
	s_lshr_b32 s8, s9, 5
	s_mul_i32 s28, s8, 11
	s_lshr_b32 s28, s28, 5
	s_mul_i32 s38, s28, 3
	s_sub_i32 s38, s8, s38
	s_cmp_lt_u32 s28, 6
	s_cbranch_scc0 .Lperm_hi_b
	s_mul_i32 s8, s28, 11
	s_lshr_b32 s8, s8, 5
	s_mul_i32 s8, s8, 3
	s_sub_i32 s8, s28, s8
	s_add_i32 s39, s28, 14
	s_cmp_eq_u32 s38, s8
	s_cbranch_scc1 .Lperm_done_b
	s_cmp_gt_u32 s38, s8
	s_cselect_b32 s8, 1, 0
	s_sub_i32 s38, s38, s8
	s_lshl_b32 s39, s28, 1
	s_add_i32 s39, s39, s38
	s_branch .Lperm_done_b
.Lperm_hi_b:
	s_lshl_b32 s39, s28, 1
	s_add_i32 s39, s39, s38
	s_add_i32 s8, s28, 6
	s_add_i32 s39, s39, 7
	s_cmp_eq_u32 s38, 0
	s_cselect_b32 s39, s8, s39
